# in-proj V^T unit order: XCD-7 chunk reversed so its padded-token tiles (slow statistics epilogue) leave the last round of layer 0; plus previous stack
# speedup vs baseline: 1.0227x; 1.0074x over previous
.LBB0_89:
	s_lshl_b32 s4, s7, 3
	v_cvt_f32_u32_e32 v1, s4
	s_sub_i32 s7, 0, s4
	s_ashr_i32 s5, s45, 3
	s_add_i32 s5, s46, s5
	s_lshl_b32 s46, s46, 1
	s_add_i32 s46, s46, s66
	s_sub_i32 s46, s46, s5
	s_add_i32 s46, s46, -1
	s_cmp_eq_u32 s47, 7
	s_cselect_b32 s46, s46, s5
	s_cmp_eq_u32 s63, 1
	s_cselect_b32 s5, s46, s5
	v_rcp_iflag_f32_e32 v1, v1
	s_abs_i32 s46, s5
	s_ashr_i32 s45, s5, 31
	v_mul_f32_e32 v1, 0x4f7ffffe, v1
	v_cvt_u32_f32_e32 v1, v1
	s_nop 0
	v_readfirstlane_b32 s47, v1
	s_mul_i32 s7, s7, s47
	s_mul_hi_u32 s7, s47, s7
	s_add_i32 s47, s47, s7
	s_mul_hi_u32 s7, s46, s47
	s_mul_i32 s47, s7, s4
	s_sub_i32 s46, s46, s47
	s_add_i32 s65, s7, 1
	s_sub_i32 s47, s46, s4
	s_cmp_ge_u32 s46, s4
	s_cselect_b32 s7, s65, s7
	s_cselect_b32 s46, s47, s46
	s_add_i32 s47, s7, 1
	s_cmp_ge_u32 s46, s4
	s_cselect_b32 s7, s47, s7
	s_xor_b32 s7, s7, s45
	s_sub_i32 s7, s7, s45
	s_lshl_b32 s45, s7, 3
	s_sub_i32 s6, s6, s45
	s_min_i32 s6, s6, 8
	s_abs_i32 s46, s6
	v_cvt_f32_u32_e32 v1, s46
	s_sub_i32 s47, 0, s46
	s_mul_i32 s7, s7, s4
	s_sub_i32 s4, s5, s7
	v_rcp_iflag_f32_e32 v1, v1
	s_abs_i32 s5, s4
	s_xor_b32 s7, s4, s6
	s_ashr_i32 s7, s7, 31
	v_mul_f32_e32 v1, 0x4f7ffffe, v1
	v_cvt_u32_f32_e32 v1, v1
	s_nop 0
	v_readfirstlane_b32 s65, v1
	s_mul_i32 s47, s47, s65
	s_mul_hi_u32 s47, s65, s47
	s_add_i32 s65, s65, s47
	s_mul_hi_u32 s47, s5, s65
	s_mul_i32 s65, s47, s46
	s_sub_i32 s5, s5, s65
	s_add_i32 s66, s47, 1
	s_sub_i32 s65, s5, s46
	s_cmp_ge_u32 s5, s46
	s_cselect_b32 s47, s66, s47
	s_cselect_b32 s5, s65, s5
	s_add_i32 s65, s47, 1
	s_cmp_ge_u32 s5, s46
	s_cselect_b32 s5, s65, s47
	s_xor_b32 s5, s5, s7
	s_sub_i32 s94, s5, s7
	s_mul_i32 s5, s94, s6
	s_sub_i32 s4, s4, s5
	s_add_i32 s6, s4, s45
